# non-temporal loads also for the fused-epilogue residual rows and attention Q fragments
# baseline (speedup 1.0000x reference)
.Latt_half_3:
	s_add_i32 s7, s5, 128
	s_and_b32 s7, s7, 511
	s_lshl_b32 s7, s7, 7
	s_add_i32 m0, s7, s9
	s_add_i32 s7, s6, 128
	v_add_u32_e32 v0, s7, v14
	v_lshlrev_b32_e32 v0, s28, v0
	v_add_u32_e32 v0, s29, v0
	v_max_i32_e32 v0, 0, v0
	v_lshl_or_b32 v2, v0, 7, v15
	v_lshl_add_u64 v[42:43], s[38:39], 0, v[2:3]
	global_load_lds_dwordx4 v[42:43], off nt
	s_add_i32 s7, s5, 192
	s_and_b32 s7, s7, 511
	s_lshl_b32 s7, s7, 7
	s_add_i32 m0, s7, s9
	s_add_i32 s7, s6, 192
	v_add_u32_e32 v0, s7, v14
	v_lshlrev_b32_e32 v0, s28, v0
	v_add_u32_e32 v0, s29, v0
	v_max_i32_e32 v0, 0, v0
	v_lshl_or_b32 v2, v0, 7, v15
	v_lshl_add_u64 v[44:45], s[38:39], 0, v[2:3]
	global_load_lds_dwordx4 v[44:45], off nt
	s_lshl_b32 s5, s30, 7
	v_add_u32_e32 v82, s5, v17
	v_lshlrev_b32_e32 v82, s28, v82
	v_add_u32_e32 v82, s29, v82
	v_lshl_add_u32 v1, v82, 11, v18
	global_load_dwordx4 v[48:51], v1, s[40:41] nt
	global_load_dwordx4 v[52:55], v1, s[40:41] offset:64 nt
	s_cmp_lt_u32 s4, 16
	s_cbranch_scc1 .Latt_odummy_4
	v_lshl_add_u32 v1, v82, 11, v19
	global_load_dwordx2 v[64:65], v1, s[42:43] offset:0
	global_load_dwordx2 v[66:67], v1, s[42:43] offset:32
	global_load_dwordx2 v[68:69], v1, s[42:43] offset:64
	global_load_dwordx2 v[70:71], v1, s[42:43] offset:96
	v_lshlrev_b32_e32 v0, 2, v82
	global_load_dword v80, v0, s[44:45]
	s_branch .Latt_odone_5

.Latt_odone_5:
	s_mov_b32 s4, 1
	s_lshr_b32 s11, s4, 4
	s_and_b32 s12, s4, 15
	s_lshl_b32 s28, s11, 1
	s_lshl_b32 s13, s64, 4
	s_add_i32 s13, s13, s12
	s_lshr_b32 s14, s12, 2
	s_and_b32 s15, s12, 3
	s_lshl_b32 s16, s64, 2
	s_add_i32 s15, s16, s15
	s_cmp_eq_u32 s11, 1
	s_cselect_b32 s29, s14, 0
	s_cselect_b32 s30, s15, s13
	s_cmp_eq_u32 s11, 2
	s_cselect_b32 s29, s12, s29
	s_cselect_b32 s30, s64, s30
	s_lshl_b32 s5, s30, 7
	v_add_u32_e32 v82, s5, v17
	v_lshlrev_b32_e32 v82, s28, v82
	v_add_u32_e32 v82, s29, v82
	v_lshl_add_u32 v1, v82, 11, v18
	global_load_dwordx4 v[56:59], v1, s[40:41] nt
	global_load_dwordx4 v[60:63], v1, s[40:41] offset:64 nt
	s_cmp_lt_u32 s4, 16
	s_cbranch_scc1 .Latt_odummy_6
	v_lshl_add_u32 v1, v82, 11, v19
	global_load_dwordx2 v[72:73], v1, s[42:43] offset:0
	global_load_dwordx2 v[74:75], v1, s[42:43] offset:32
	global_load_dwordx2 v[76:77], v1, s[42:43] offset:64
	global_load_dwordx2 v[78:79], v1, s[42:43] offset:96
	v_lshlrev_b32_e32 v0, 2, v82
	global_load_dword v81, v0, s[44:45]
	s_branch .Latt_odone_7

.Latt_half_22:
	s_add_i32 s7, s5, 128
	s_and_b32 s7, s7, 511
	s_lshl_b32 s7, s7, 7
	s_add_i32 m0, s7, s49
	s_add_i32 s7, s6, 128
	v_add_u32_e32 v0, s7, v14
	v_lshlrev_b32_e32 v0, s28, v0
	v_add_u32_e32 v0, s29, v0
	v_max_i32_e32 v0, 0, v0
	v_lshl_or_b32 v2, v0, 7, v15
	v_lshl_add_u64 v[42:43], s[50:51], 0, v[2:3]
	global_load_lds_dwordx4 v[42:43], off nt
	s_add_i32 s7, s5, 192
	s_and_b32 s7, s7, 511
	s_lshl_b32 s7, s7, 7
	s_add_i32 m0, s7, s49
	s_add_i32 s7, s6, 192
	v_add_u32_e32 v0, s7, v14
	v_lshlrev_b32_e32 v0, s28, v0
	v_add_u32_e32 v0, s29, v0
	v_max_i32_e32 v0, 0, v0
	v_lshl_or_b32 v2, v0, 7, v15
	v_lshl_add_u64 v[44:45], s[50:51], 0, v[2:3]
	global_load_lds_dwordx4 v[44:45], off nt
	s_add_i32 s4, s53, 2
	s_min_u32 s4, s4, 47
	s_lshr_b32 s11, s4, 4
	s_and_b32 s12, s4, 15
	s_lshl_b32 s8, s11, 1
	s_lshl_b32 s13, s64, 4
	s_add_i32 s13, s13, s12
	s_lshr_b32 s14, s12, 2
	s_and_b32 s15, s12, 3
	s_lshl_b32 s16, s64, 2
	s_add_i32 s15, s16, s15
	s_cmp_eq_u32 s11, 1
	s_cselect_b32 s17, s14, 0
	s_cselect_b32 s10, s15, s13
	s_cmp_eq_u32 s11, 2
	s_cselect_b32 s17, s12, s17
	s_cselect_b32 s10, s64, s10
	s_lshl_b32 s5, s10, 7
	v_add_u32_e32 v82, s5, v17
	v_lshlrev_b32_e32 v82, s8, v82
	v_add_u32_e32 v82, s17, v82
	v_lshl_add_u32 v1, v82, 11, v18
	global_load_dwordx4 v[48:51], v1, s[40:41] nt
	global_load_dwordx4 v[52:55], v1, s[40:41] offset:64 nt
	s_add_i32 s5, s91, 0
	s_and_b32 s5, s5, 31
	s_lshl_b32 s5, s5, 11
	v_add_u32_e32 v37, s5, v6
	v_add_u32_e32 v38, s5, v7
	v_add_u32_e32 v39, s5, v8
	v_add_u32_e32 v40, s5, v9
	ds_read_b64_tr_b16 v[84:85], v37
	ds_read_b64_tr_b16 v[88:89], v38
	ds_read_b64_tr_b16 v[92:93], v39
	ds_read_b64_tr_b16 v[96:97], v40
	s_add_i32 s5, s91, 1
	s_and_b32 s5, s5, 31
	s_lshl_b32 s5, s5, 11
	v_add_u32_e32 v37, s5, v6
	v_add_u32_e32 v38, s5, v7
	v_add_u32_e32 v39, s5, v8
	v_add_u32_e32 v40, s5, v9
	ds_read_b64_tr_b16 v[86:87], v37
	ds_read_b64_tr_b16 v[90:91], v38
	ds_read_b64_tr_b16 v[94:95], v39
	ds_read_b64_tr_b16 v[98:99], v40
	s_add_i32 s5, s91, 2
	s_and_b32 s5, s5, 31
	s_lshl_b32 s5, s5, 11
	v_add_u32_e32 v37, s5, v6
	v_add_u32_e32 v38, s5, v7
	v_add_u32_e32 v39, s5, v8
	v_add_u32_e32 v40, s5, v9
	ds_read_b64_tr_b16 v[100:101], v37
	ds_read_b64_tr_b16 v[104:105], v38
	ds_read_b64_tr_b16 v[108:109], v39
	ds_read_b64_tr_b16 v[112:113], v40
	s_add_i32 s5, s91, 3
	s_and_b32 s5, s5, 31
	s_lshl_b32 s5, s5, 11
	v_add_u32_e32 v37, s5, v6
	v_add_u32_e32 v38, s5, v7
	v_add_u32_e32 v39, s5, v8
	v_add_u32_e32 v40, s5, v9
	ds_read_b64_tr_b16 v[102:103], v37
	ds_read_b64_tr_b16 v[106:107], v38
	ds_read_b64_tr_b16 v[110:111], v39
	ds_read_b64_tr_b16 v[114:115], v40
	s_waitcnt lgkmcnt(8)
	v_mfma_f32_16x16x32_bf16 v[228:231], v[84:87], v[172:175], 0
	v_mfma_f32_16x16x32_bf16 v[232:235], v[88:91], v[172:175], 0
	v_mfma_f32_16x16x32_bf16 v[236:239], v[92:95], v[172:175], 0
	v_mfma_f32_16x16x32_bf16 v[240:243], v[96:99], v[172:175], 0
	s_add_i32 s5, s91, 4
	s_and_b32 s5, s5, 31
	s_lshl_b32 s5, s5, 11
	v_add_u32_e32 v37, s5, v6
	v_add_u32_e32 v38, s5, v7
	v_add_u32_e32 v39, s5, v8
	v_add_u32_e32 v40, s5, v9
	ds_read_b64_tr_b16 v[84:85], v37
	ds_read_b64_tr_b16 v[88:89], v38
	ds_read_b64_tr_b16 v[92:93], v39
	ds_read_b64_tr_b16 v[96:97], v40
	s_add_i32 s5, s91, 5
	s_and_b32 s5, s5, 31
	s_lshl_b32 s5, s5, 11
	v_add_u32_e32 v37, s5, v6
	v_add_u32_e32 v38, s5, v7
	v_add_u32_e32 v39, s5, v8
	v_add_u32_e32 v40, s5, v9
	ds_read_b64_tr_b16 v[86:87], v37
	ds_read_b64_tr_b16 v[90:91], v38
	ds_read_b64_tr_b16 v[94:95], v39
	ds_read_b64_tr_b16 v[98:99], v40
	s_waitcnt lgkmcnt(8)
	v_mfma_f32_16x16x32_bf16 v[228:231], v[100:103], v[176:179], v[228:231]
	v_mfma_f32_16x16x32_bf16 v[232:235], v[104:107], v[176:179], v[232:235]
	v_mfma_f32_16x16x32_bf16 v[236:239], v[108:111], v[176:179], v[236:239]
	v_mfma_f32_16x16x32_bf16 v[240:243], v[112:115], v[176:179], v[240:243]
	s_add_i32 s5, s91, 6
	s_and_b32 s5, s5, 31
	s_lshl_b32 s5, s5, 11
	v_add_u32_e32 v37, s5, v6
	v_add_u32_e32 v38, s5, v7
	v_add_u32_e32 v39, s5, v8
	v_add_u32_e32 v40, s5, v9
	ds_read_b64_tr_b16 v[100:101], v37
	ds_read_b64_tr_b16 v[104:105], v38
	ds_read_b64_tr_b16 v[108:109], v39
	ds_read_b64_tr_b16 v[112:113], v40
	s_add_i32 s5, s91, 7
	s_and_b32 s5, s5, 31
	s_lshl_b32 s5, s5, 11
	v_add_u32_e32 v37, s5, v6
	v_add_u32_e32 v38, s5, v7
	v_add_u32_e32 v39, s5, v8
	v_add_u32_e32 v40, s5, v9
	ds_read_b64_tr_b16 v[102:103], v37
	ds_read_b64_tr_b16 v[106:107], v38
	ds_read_b64_tr_b16 v[110:111], v39
	ds_read_b64_tr_b16 v[114:115], v40
	s_waitcnt lgkmcnt(8)
	v_mfma_f32_16x16x32_bf16 v[228:231], v[84:87], v[180:183], v[228:231]
	v_mfma_f32_16x16x32_bf16 v[232:235], v[88:91], v[180:183], v[232:235]
	v_mfma_f32_16x16x32_bf16 v[236:239], v[92:95], v[180:183], v[236:239]
	v_mfma_f32_16x16x32_bf16 v[240:243], v[96:99], v[180:183], v[240:243]
	s_add_i32 s5, s91, 8
	s_and_b32 s5, s5, 31
	s_lshl_b32 s5, s5, 11
	v_add_u32_e32 v37, s5, v6
	v_add_u32_e32 v38, s5, v7
	v_add_u32_e32 v39, s5, v8
	v_add_u32_e32 v40, s5, v9
	ds_read_b64_tr_b16 v[84:85], v37
	ds_read_b64_tr_b16 v[88:89], v38
	ds_read_b64_tr_b16 v[92:93], v39
	ds_read_b64_tr_b16 v[96:97], v40
	s_add_i32 s5, s67, 9
	s_min_u32 s5, s5, 15
	s_lshl_b32 s6, s90, 3
	s_add_i32 s5, s5, s6
	s_and_b32 s5, s5, 31
	s_lshl_b32 s5, s5, 11
	v_add_u32_e32 v37, s5, v6
	v_add_u32_e32 v38, s5, v7
	v_add_u32_e32 v39, s5, v8
	v_add_u32_e32 v40, s5, v9
	ds_read_b64_tr_b16 v[86:87], v37
	ds_read_b64_tr_b16 v[90:91], v38
	ds_read_b64_tr_b16 v[94:95], v39
	ds_read_b64_tr_b16 v[98:99], v40
	s_waitcnt lgkmcnt(8)
	v_mfma_f32_16x16x32_bf16 v[228:231], v[100:103], v[184:187], v[228:231]
	v_mfma_f32_16x16x32_bf16 v[232:235], v[104:107], v[184:187], v[232:235]
	v_mfma_f32_16x16x32_bf16 v[236:239], v[108:111], v[184:187], v[236:239]
	v_mfma_f32_16x16x32_bf16 v[240:243], v[112:115], v[184:187], v[240:243]
	s_waitcnt lgkmcnt(0)
	v_mfma_f32_16x16x32_bf16 v[228:231], v[84:87], v[188:191], v[228:231]
	v_mfma_f32_16x16x32_bf16 v[232:235], v[88:91], v[188:191], v[232:235]
	v_mfma_f32_16x16x32_bf16 v[236:239], v[92:95], v[188:191], v[236:239]
	v_mfma_f32_16x16x32_bf16 v[240:243], v[96:99], v[188:191], v[240:243]
	v_mov_b32_e32 v0, v36
	v_mov_b32_e32 v1, v36
	s_nop 1
	v_permlane16_swap_b32_e32 v0, v1
	s_nop 1
	v_add_f32_e32 v36, v0, v1
	v_mov_b32_e32 v0, v36
	v_mov_b32_e32 v1, v36
	s_nop 1
	v_permlane32_swap_b32_e32 v0, v1
	s_nop 1
	v_add_f32_e32 v36, v0, v1
	s_cmp_lt_u32 s53, 16
	s_cbranch_scc0 .Latt_hasprev_23
	v_mov_b32_e32 v80, v223
	v_mov_b32_e32 v64, 0
	v_mov_b32_e32 v65, 0
	v_mov_b32_e32 v66, 0
	v_mov_b32_e32 v67, 0
	v_mov_b32_e32 v68, 0
	v_mov_b32_e32 v69, 0
	v_mov_b32_e32 v70, 0
	v_mov_b32_e32 v71, 0

.Latt_half_40:
	s_add_i32 s7, s5, 128
	s_and_b32 s7, s7, 511
	s_lshl_b32 s7, s7, 7
	s_add_i32 m0, s7, s49
	s_add_i32 s7, s6, 128
	v_add_u32_e32 v0, s7, v14
	v_lshlrev_b32_e32 v0, s28, v0
	v_add_u32_e32 v0, s29, v0
	v_max_i32_e32 v0, 0, v0
	v_lshl_or_b32 v2, v0, 7, v15
	v_lshl_add_u64 v[42:43], s[50:51], 0, v[2:3]
	global_load_lds_dwordx4 v[42:43], off nt
	s_add_i32 s7, s5, 192
	s_and_b32 s7, s7, 511
	s_lshl_b32 s7, s7, 7
	s_add_i32 m0, s7, s49
	s_add_i32 s7, s6, 192
	v_add_u32_e32 v0, s7, v14
	v_lshlrev_b32_e32 v0, s28, v0
	v_add_u32_e32 v0, s29, v0
	v_max_i32_e32 v0, 0, v0
	v_lshl_or_b32 v2, v0, 7, v15
	v_lshl_add_u64 v[44:45], s[50:51], 0, v[2:3]
	global_load_lds_dwordx4 v[44:45], off nt
	s_add_i32 s4, s9, 2
	s_min_u32 s4, s4, 47
	s_lshr_b32 s11, s4, 4
	s_and_b32 s12, s4, 15
	s_lshl_b32 s8, s11, 1
	s_lshl_b32 s13, s64, 4
	s_add_i32 s13, s13, s12
	s_lshr_b32 s14, s12, 2
	s_and_b32 s15, s12, 3
	s_lshl_b32 s16, s64, 2
	s_add_i32 s15, s16, s15
	s_cmp_eq_u32 s11, 1
	s_cselect_b32 s17, s14, 0
	s_cselect_b32 s10, s15, s13
	s_cmp_eq_u32 s11, 2
	s_cselect_b32 s17, s12, s17
	s_cselect_b32 s10, s64, s10
	s_lshl_b32 s5, s10, 7
	v_add_u32_e32 v82, s5, v17
	v_lshlrev_b32_e32 v82, s8, v82
	v_add_u32_e32 v82, s17, v82
	v_lshl_add_u32 v1, v82, 11, v18
	global_load_dwordx4 v[56:59], v1, s[40:41] nt
	global_load_dwordx4 v[60:63], v1, s[40:41] offset:64 nt
	s_add_i32 s5, s91, 0
	s_and_b32 s5, s5, 31
	s_lshl_b32 s5, s5, 11
	v_add_u32_e32 v37, s5, v6
	v_add_u32_e32 v38, s5, v7
	v_add_u32_e32 v39, s5, v8
	v_add_u32_e32 v40, s5, v9
	ds_read_b64_tr_b16 v[84:85], v37
	ds_read_b64_tr_b16 v[88:89], v38
	ds_read_b64_tr_b16 v[92:93], v39
	ds_read_b64_tr_b16 v[96:97], v40
	s_add_i32 s5, s91, 1
	s_and_b32 s5, s5, 31
	s_lshl_b32 s5, s5, 11
	v_add_u32_e32 v37, s5, v6
	v_add_u32_e32 v38, s5, v7
	v_add_u32_e32 v39, s5, v8
	v_add_u32_e32 v40, s5, v9
	ds_read_b64_tr_b16 v[86:87], v37
	ds_read_b64_tr_b16 v[90:91], v38
	ds_read_b64_tr_b16 v[94:95], v39
	ds_read_b64_tr_b16 v[98:99], v40
	s_add_i32 s5, s91, 2
	s_and_b32 s5, s5, 31
	s_lshl_b32 s5, s5, 11
	v_add_u32_e32 v37, s5, v6
	v_add_u32_e32 v38, s5, v7
	v_add_u32_e32 v39, s5, v8
	v_add_u32_e32 v40, s5, v9
	ds_read_b64_tr_b16 v[100:101], v37
	ds_read_b64_tr_b16 v[104:105], v38
	ds_read_b64_tr_b16 v[108:109], v39
	ds_read_b64_tr_b16 v[112:113], v40
	s_add_i32 s5, s91, 3
	s_and_b32 s5, s5, 31
	s_lshl_b32 s5, s5, 11
	v_add_u32_e32 v37, s5, v6
	v_add_u32_e32 v38, s5, v7
	v_add_u32_e32 v39, s5, v8
	v_add_u32_e32 v40, s5, v9
	ds_read_b64_tr_b16 v[102:103], v37
	ds_read_b64_tr_b16 v[106:107], v38
	ds_read_b64_tr_b16 v[110:111], v39
	ds_read_b64_tr_b16 v[114:115], v40
	s_waitcnt lgkmcnt(8)
	v_mfma_f32_16x16x32_bf16 v[228:231], v[84:87], v[172:175], 0
	v_mfma_f32_16x16x32_bf16 v[232:235], v[88:91], v[172:175], 0
	v_mfma_f32_16x16x32_bf16 v[236:239], v[92:95], v[172:175], 0
	v_mfma_f32_16x16x32_bf16 v[240:243], v[96:99], v[172:175], 0
	s_add_i32 s5, s91, 4
	s_and_b32 s5, s5, 31
	s_lshl_b32 s5, s5, 11
	v_add_u32_e32 v37, s5, v6
	v_add_u32_e32 v38, s5, v7
	v_add_u32_e32 v39, s5, v8
	v_add_u32_e32 v40, s5, v9
	ds_read_b64_tr_b16 v[84:85], v37
	ds_read_b64_tr_b16 v[88:89], v38
	ds_read_b64_tr_b16 v[92:93], v39
	ds_read_b64_tr_b16 v[96:97], v40
	s_add_i32 s5, s91, 5
	s_and_b32 s5, s5, 31
	s_lshl_b32 s5, s5, 11
	v_add_u32_e32 v37, s5, v6
	v_add_u32_e32 v38, s5, v7
	v_add_u32_e32 v39, s5, v8
	v_add_u32_e32 v40, s5, v9
	ds_read_b64_tr_b16 v[86:87], v37
	ds_read_b64_tr_b16 v[90:91], v38
	ds_read_b64_tr_b16 v[94:95], v39
	ds_read_b64_tr_b16 v[98:99], v40
	s_waitcnt lgkmcnt(8)
	v_mfma_f32_16x16x32_bf16 v[228:231], v[100:103], v[176:179], v[228:231]
	v_mfma_f32_16x16x32_bf16 v[232:235], v[104:107], v[176:179], v[232:235]
	v_mfma_f32_16x16x32_bf16 v[236:239], v[108:111], v[176:179], v[236:239]
	v_mfma_f32_16x16x32_bf16 v[240:243], v[112:115], v[176:179], v[240:243]
	s_add_i32 s5, s91, 6
	s_and_b32 s5, s5, 31
	s_lshl_b32 s5, s5, 11
	v_add_u32_e32 v37, s5, v6
	v_add_u32_e32 v38, s5, v7
	v_add_u32_e32 v39, s5, v8
	v_add_u32_e32 v40, s5, v9
	ds_read_b64_tr_b16 v[100:101], v37
	ds_read_b64_tr_b16 v[104:105], v38
	ds_read_b64_tr_b16 v[108:109], v39
	ds_read_b64_tr_b16 v[112:113], v40
	s_add_i32 s5, s91, 7
	s_and_b32 s5, s5, 31
	s_lshl_b32 s5, s5, 11
	v_add_u32_e32 v37, s5, v6
	v_add_u32_e32 v38, s5, v7
	v_add_u32_e32 v39, s5, v8
	v_add_u32_e32 v40, s5, v9
	ds_read_b64_tr_b16 v[102:103], v37
	ds_read_b64_tr_b16 v[106:107], v38
	ds_read_b64_tr_b16 v[110:111], v39
	ds_read_b64_tr_b16 v[114:115], v40
	s_waitcnt lgkmcnt(8)
	v_mfma_f32_16x16x32_bf16 v[228:231], v[84:87], v[180:183], v[228:231]
	v_mfma_f32_16x16x32_bf16 v[232:235], v[88:91], v[180:183], v[232:235]
	v_mfma_f32_16x16x32_bf16 v[236:239], v[92:95], v[180:183], v[236:239]
	v_mfma_f32_16x16x32_bf16 v[240:243], v[96:99], v[180:183], v[240:243]
	s_add_i32 s5, s91, 8
	s_and_b32 s5, s5, 31
	s_lshl_b32 s5, s5, 11
	v_add_u32_e32 v37, s5, v6
	v_add_u32_e32 v38, s5, v7
	v_add_u32_e32 v39, s5, v8
	v_add_u32_e32 v40, s5, v9
	ds_read_b64_tr_b16 v[84:85], v37
	ds_read_b64_tr_b16 v[88:89], v38
	ds_read_b64_tr_b16 v[92:93], v39
	ds_read_b64_tr_b16 v[96:97], v40
	s_add_i32 s5, s67, 9
	s_min_u32 s5, s5, 15
	s_lshl_b32 s6, s90, 3
	s_add_i32 s5, s5, s6
	s_and_b32 s5, s5, 31
	s_lshl_b32 s5, s5, 11
	v_add_u32_e32 v37, s5, v6
	v_add_u32_e32 v38, s5, v7
	v_add_u32_e32 v39, s5, v8
	v_add_u32_e32 v40, s5, v9
	ds_read_b64_tr_b16 v[86:87], v37
	ds_read_b64_tr_b16 v[90:91], v38
	ds_read_b64_tr_b16 v[94:95], v39
	ds_read_b64_tr_b16 v[98:99], v40
	s_waitcnt lgkmcnt(8)
	v_mfma_f32_16x16x32_bf16 v[228:231], v[100:103], v[184:187], v[228:231]
	v_mfma_f32_16x16x32_bf16 v[232:235], v[104:107], v[184:187], v[232:235]
	v_mfma_f32_16x16x32_bf16 v[236:239], v[108:111], v[184:187], v[236:239]
	v_mfma_f32_16x16x32_bf16 v[240:243], v[112:115], v[184:187], v[240:243]
	s_waitcnt lgkmcnt(0)
	v_mfma_f32_16x16x32_bf16 v[228:231], v[84:87], v[188:191], v[228:231]
	v_mfma_f32_16x16x32_bf16 v[232:235], v[88:91], v[188:191], v[232:235]
	v_mfma_f32_16x16x32_bf16 v[236:239], v[92:95], v[188:191], v[236:239]
	v_mfma_f32_16x16x32_bf16 v[240:243], v[96:99], v[188:191], v[240:243]
	v_mov_b32_e32 v0, v36
	v_mov_b32_e32 v1, v36
	s_nop 1
	v_permlane16_swap_b32_e32 v0, v1
	s_nop 1
	v_add_f32_e32 v36, v0, v1
	v_mov_b32_e32 v0, v36
	v_mov_b32_e32 v1, v36
	s_nop 1
	v_permlane32_swap_b32_e32 v0, v1
	s_nop 1
	v_add_f32_e32 v36, v0, v1
	s_cmp_lt_u32 s9, 16
	s_cbranch_scc0 .Latt_hasprev_41
	v_mov_b32_e32 v81, v223
	v_mov_b32_e32 v72, 0
	v_mov_b32_e32 v73, 0
	v_mov_b32_e32 v74, 0
	v_mov_b32_e32 v75, 0
	v_mov_b32_e32 v76, 0
	v_mov_b32_e32 v77, 0
	v_mov_b32_e32 v78, 0
	v_mov_b32_e32 v79, 0

.LBB0_352:
	s_add_u32 s0, s50, 0x1ea20000
	s_addc_u32 s1, s51, 0
	s_lshl_b32 s10, s4, 8
	s_or_b32 s11, s10, 0x80
	v_add_u32_e32 v0, s10, v229
	v_ashrrev_i32_e32 v1, 31, v0
	v_add_u32_e32 v88, s11, v229
	v_lshl_add_u64 v[84:85], v[202:203], 1, s[54:55]
	v_lshl_add_u64 v[86:87], v[0:1], 2, s[0:1]
	v_ashrrev_i32_e32 v89, 31, v88
	v_lshlrev_b64 v[0:1], 11, v[0:1]
	v_or_b32_e32 v2, 16, v229
	v_lshl_add_u64 v[88:89], v[88:89], 2, s[0:1]
	v_lshl_add_u64 v[0:1], v[84:85], 0, v[0:1]
	global_load_dword v220, v[86:87], off
	global_load_dword v210, v[88:89], off
	global_load_dwordx4 v[176:179], v[0:1], off nt
	v_add_u32_e32 v86, s10, v2
	v_add_u32_e32 v90, s11, v2
	v_ashrrev_i32_e32 v87, 31, v86
	v_ashrrev_i32_e32 v91, 31, v90
	v_lshl_add_u64 v[88:89], v[86:87], 2, s[0:1]
	v_lshl_add_u64 v[90:91], v[90:91], 2, s[0:1]
	global_load_dwordx4 v[172:175], v[0:1], off offset:256 nt
	global_load_dword v218, v[88:89], off
	global_load_dword v208, v[90:91], off
	v_lshlrev_b64 v[0:1], 11, v[86:87]
	v_lshl_add_u64 v[0:1], v[84:85], 0, v[0:1]
	v_or_b32_e32 v2, 32, v229
	global_load_dwordx4 v[168:171], v[0:1], off nt
	global_load_dwordx4 v[164:167], v[0:1], off offset:256 nt
	v_add_u32_e32 v0, s10, v2
	v_ashrrev_i32_e32 v1, 31, v0
	v_add_u32_e32 v88, s11, v2
	v_lshl_add_u64 v[86:87], v[0:1], 2, s[0:1]
	v_ashrrev_i32_e32 v89, 31, v88
	v_lshlrev_b64 v[0:1], 11, v[0:1]
	v_or_b32_e32 v90, 48, v229
	v_lshl_add_u64 v[88:89], v[88:89], 2, s[0:1]
	v_lshl_add_u64 v[0:1], v[84:85], 0, v[0:1]
	global_load_dword v216, v[86:87], off
	global_load_dword v2, v[88:89], off
	global_load_dwordx4 v[160:163], v[0:1], off nt
	v_add_u32_e32 v86, s10, v90
	v_ashrrev_i32_e32 v87, 31, v86
	v_add_u32_e32 v90, s11, v90
	v_lshl_add_u64 v[88:89], v[86:87], 2, s[0:1]
	v_ashrrev_i32_e32 v91, 31, v90
	v_lshlrev_b64 v[86:87], 11, v[86:87]
	v_lshl_add_u64 v[90:91], v[90:91], 2, s[0:1]
	global_load_dwordx4 v[156:159], v[0:1], off offset:256 nt
	global_load_dword v212, v[88:89], off
	s_nop 0
	global_load_dword v0, v[90:91], off
	v_lshl_add_u64 v[84:85], v[84:85], 0, v[86:87]
	global_load_dwordx4 v[152:155], v[84:85], off nt
	global_load_dwordx4 v[148:151], v[84:85], off offset:256 nt
.LBB0_353:
	s_add_u32 s0, s18, s6
	s_addc_u32 s1, s29, s7
	v_lshl_add_u64 v[84:85], v[202:203], 2, s[0:1]
	s_mov_b64 s[0:1], 0x1000
	v_lshl_add_u64 v[88:89], v[84:85], 0, s[0:1]
	s_movk_i32 s0, 0x1000
	v_add_co_u32_e32 v84, vcc, s0, v84
	v_mul_f32_e32 v182, v121, v121
	s_nop 0
	v_addc_co_u32_e32 v85, vcc, 0, v85, vcc
	global_load_dwordx4 v[96:99], v[84:85], off nt
	s_nop 0
	global_load_dwordx4 v[84:87], v[88:89], off offset:528 nt
	global_load_dwordx4 v[92:95], v[88:89], off offset:16 nt
	s_nop 0
	global_load_dwordx4 v[88:91], v[88:89], off offset:512 nt
	v_mul_f32_e32 v183, v123, v123
	v_fmac_f32_e32 v182, v120, v120
	v_fmac_f32_e32 v183, v122, v122
	v_add_f32_e32 v182, v182, v183
	v_mul_f32_e32 v183, v129, v129
	v_mul_f32_e32 v184, v131, v131
	v_fmac_f32_e32 v183, v128, v128
	v_fmac_f32_e32 v184, v130, v130
	v_add_f32_e32 v183, v183, v184
	v_add_f32_e32 v182, v182, v183
	v_mul_f32_e32 v183, v117, v117
	v_mul_f32_e32 v184, v119, v119
	v_fmac_f32_e32 v183, v116, v116
	v_fmac_f32_e32 v184, v118, v118
	v_and_b32_e32 v181, 64, v226
	v_add_f32_e32 v183, v183, v184
	v_xor_b32_e32 v1, 16, v226
	v_add_u32_e32 v181, 64, v181
	v_add_f32_e32 v182, v182, v183
	v_mul_f32_e32 v183, v125, v125
	v_mul_f32_e32 v184, v127, v127
	v_cmp_lt_i32_e32 vcc, v1, v181
	v_fmac_f32_e32 v183, v124, v124
	v_fmac_f32_e32 v184, v126, v126
	v_cndmask_b32_e32 v1, v226, v1, vcc
	v_add_f32_e32 v183, v183, v184
	v_lshlrev_b32_e32 v1, 2, v1
	v_add_f32_e32 v182, v182, v183
	v_mov_b32_e32 v183, v182
	s_nop 1
	v_permlane16_swap_b32_e32 v183, v182
	v_xor_b32_e32 v184, 32, v226
	v_cmp_lt_i32_e32 vcc, v184, v181
	v_and_b32_e32 v217, 63, v180
	s_lshl_b32 s0, s5, 2
	v_cndmask_b32_e32 v181, v226, v184, vcc
	v_lshlrev_b32_e32 v228, 2, v181
	s_waitcnt lgkmcnt(0)
	v_add_f32_e32 v181, v182, v183
	v_mov_b32_e32 v182, v181
	s_nop 1
	v_permlane32_swap_b32_e32 v182, v181
	v_cmp_gt_u32_e64 s[38:39], 16, v217
	s_add_i32 s10, s0, 0
	s_and_saveexec_b64 s[0:1], s[38:39]
	s_cbranch_execz .LBB0_355
	s_lshl_b32 s5, s21, 10
	s_add_i32 s5, s10, s5
	v_lshl_add_u32 v183, v193, 4, s5
	s_waitcnt lgkmcnt(0)
	v_add_f32_e32 v181, v181, v182
	ds_write_b32 v183, v181

.LBB0_379:
	s_or_b64 exec, exec, s[0:1]
	s_waitcnt lgkmcnt(0)
	s_barrier
	v_lshl_add_u32 v227, v229, 2, 0
	ds_read_b32 v222, v227 offset:4096
	v_add_u32_e32 v214, s7, v229
	v_ashrrev_i32_e32 v215, 31, v214
	v_lshlrev_b64 v[180:181], 10, v[214:215]
	v_lshl_add_u64 v[204:205], v[202:203], 0, v[180:181]
	v_cndmask_b32_e64 v180, 0, 1, s[8:9]
	v_cmp_ne_u32_e64 s[40:41], 1, v180
	s_andn2_b64 vcc, exec, s[8:9]
	v_lshl_add_u64 v[224:225], v[204:205], 2, s[52:53]
	s_cbranch_vccnz .LBB0_456
	global_load_dwordx4 v[184:187], v[224:225], off offset:16 nt
	global_load_dwordx4 v[180:183], v[224:225], off nt
	s_cbranch_execnz .LBB0_382

.LBB0_382:
	s_and_b64 vcc, exec, s[40:41]
	s_cbranch_vccnz .LBB0_457
	global_load_dwordx4 v[188:191], v[224:225], off offset:528 nt
	global_load_dwordx4 v[176:179], v[224:225], off offset:512 nt
	s_cbranch_execnz .LBB0_385

.LBB0_385:
	s_waitcnt lgkmcnt(0)
	v_pk_mul_f32 v[122:123], v[122:123], v[222:223] op_sel_hi:[1,0]
	v_pk_mul_f32 v[120:121], v[120:121], v[222:223] op_sel_hi:[1,0]
	v_pk_mul_f32 v[130:131], v[130:131], v[222:223] op_sel_hi:[1,0]
	v_pk_mul_f32 v[128:129], v[128:129], v[222:223] op_sel_hi:[1,0]
	v_pk_mul_f32 v[118:119], v[118:119], v[222:223] op_sel_hi:[1,0]
	v_pk_mul_f32 v[116:117], v[116:117], v[222:223] op_sel_hi:[1,0]
	v_pk_mul_f32 v[126:127], v[126:127], v[222:223] op_sel_hi:[1,0]
	v_pk_mul_f32 v[124:125], v[124:125], v[222:223] op_sel_hi:[1,0]
	s_waitcnt vmcnt(0)
	v_pk_fma_f32 v[122:123], v[98:99], v[122:123], v[182:183]
	v_pk_fma_f32 v[120:121], v[96:97], v[120:121], v[180:181]
	v_pk_fma_f32 v[128:129], v[92:93], v[128:129], v[184:185]
	v_pk_fma_f32 v[130:131], v[94:95], v[130:131], v[186:187]
	v_pk_fma_f32 v[118:119], v[90:91], v[118:119], v[178:179]
	v_pk_fma_f32 v[116:117], v[88:89], v[116:117], v[176:177]
	v_pk_fma_f32 v[124:125], v[84:85], v[124:125], v[188:189]
	v_pk_fma_f32 v[126:127], v[86:87], v[126:127], v[190:191]
	v_add3_u32 v172, s7, v229, 16
	ds_read_b32 v186, v227 offset:4160
	v_ashrrev_i32_e32 v173, 31, v172
	v_lshlrev_b64 v[172:173], 10, v[172:173]
	v_lshl_add_u64 v[184:185], v[202:203], 0, v[172:173]
	s_and_b64 vcc, exec, s[40:41]
	v_lshl_add_u64 v[188:189], v[184:185], 2, s[52:53]
	s_cbranch_vccnz .LBB0_458
	global_load_dwordx4 v[176:179], v[188:189], off offset:16 nt
	global_load_dwordx4 v[172:175], v[188:189], off nt
	s_cbranch_execnz .LBB0_388

.LBB0_388:
	s_and_b64 vcc, exec, s[40:41]
	s_cbranch_vccnz .LBB0_459
	global_load_dwordx4 v[180:183], v[188:189], off offset:528 nt
	global_load_dwordx4 v[168:171], v[188:189], off offset:512 nt
	s_cbranch_execnz .LBB0_391

.LBB0_391:
	s_waitcnt lgkmcnt(0)
	v_pk_mul_f32 v[142:143], v[142:143], v[186:187] op_sel_hi:[1,0]
	v_pk_mul_f32 v[140:141], v[140:141], v[186:187] op_sel_hi:[1,0]
	v_pk_mul_f32 v[146:147], v[146:147], v[186:187] op_sel_hi:[1,0]
	v_pk_mul_f32 v[144:145], v[144:145], v[186:187] op_sel_hi:[1,0]
	v_pk_mul_f32 v[138:139], v[138:139], v[186:187] op_sel_hi:[1,0]
	v_pk_mul_f32 v[136:137], v[136:137], v[186:187] op_sel_hi:[1,0]
	v_pk_mul_f32 v[134:135], v[134:135], v[186:187] op_sel_hi:[1,0]
	v_pk_mul_f32 v[132:133], v[132:133], v[186:187] op_sel_hi:[1,0]
	s_waitcnt vmcnt(0)
	v_pk_fma_f32 v[142:143], v[98:99], v[142:143], v[174:175]
	v_pk_fma_f32 v[140:141], v[96:97], v[140:141], v[172:173]
	v_pk_fma_f32 v[146:147], v[94:95], v[146:147], v[178:179]
	v_pk_fma_f32 v[144:145], v[92:93], v[144:145], v[176:177]
	v_pk_fma_f32 v[138:139], v[90:91], v[138:139], v[170:171]
	v_pk_fma_f32 v[136:137], v[88:89], v[136:137], v[168:169]
	v_pk_fma_f32 v[134:135], v[86:87], v[134:135], v[182:183]
	v_pk_fma_f32 v[132:133], v[84:85], v[132:133], v[180:181]
	v_add3_u32 v164, s7, v229, 32
	ds_read_b32 v178, v227 offset:4224
	v_ashrrev_i32_e32 v165, 31, v164
	v_lshlrev_b64 v[164:165], 10, v[164:165]
	v_lshl_add_u64 v[176:177], v[202:203], 0, v[164:165]
	s_and_b64 vcc, exec, s[40:41]
	v_lshl_add_u64 v[180:181], v[176:177], 2, s[52:53]
	s_cbranch_vccnz .LBB0_460
	global_load_dwordx4 v[168:171], v[180:181], off offset:16 nt
	global_load_dwordx4 v[164:167], v[180:181], off nt
	s_cbranch_execnz .LBB0_394

.LBB0_394:
	s_and_b64 vcc, exec, s[40:41]
	s_cbranch_vccnz .LBB0_461
	global_load_dwordx4 v[172:175], v[180:181], off offset:528 nt
	global_load_dwordx4 v[160:163], v[180:181], off offset:512 nt
	s_cbranch_execnz .LBB0_397

.LBB0_397:
	s_waitcnt lgkmcnt(0)
	v_pk_mul_f32 v[114:115], v[114:115], v[178:179] op_sel_hi:[1,0]
	v_pk_mul_f32 v[112:113], v[112:113], v[178:179] op_sel_hi:[1,0]
	v_pk_mul_f32 v[110:111], v[110:111], v[178:179] op_sel_hi:[1,0]
	v_pk_mul_f32 v[108:109], v[108:109], v[178:179] op_sel_hi:[1,0]
	v_pk_mul_f32 v[106:107], v[106:107], v[178:179] op_sel_hi:[1,0]
	v_pk_mul_f32 v[104:105], v[104:105], v[178:179] op_sel_hi:[1,0]
	v_pk_mul_f32 v[102:103], v[102:103], v[178:179] op_sel_hi:[1,0]
	v_pk_mul_f32 v[100:101], v[100:101], v[178:179] op_sel_hi:[1,0]
	s_waitcnt vmcnt(0)
	v_pk_fma_f32 v[114:115], v[98:99], v[114:115], v[166:167]
	v_pk_fma_f32 v[112:113], v[96:97], v[112:113], v[164:165]
	v_pk_fma_f32 v[110:111], v[94:95], v[110:111], v[170:171]
	v_pk_fma_f32 v[108:109], v[92:93], v[108:109], v[168:169]
	v_pk_fma_f32 v[106:107], v[90:91], v[106:107], v[162:163]
	v_pk_fma_f32 v[104:105], v[88:89], v[104:105], v[160:161]
	v_pk_fma_f32 v[102:103], v[86:87], v[102:103], v[174:175]
	v_pk_fma_f32 v[100:101], v[84:85], v[100:101], v[172:173]
	v_add3_u32 v156, s7, v229, 48
	ds_read_b32 v170, v227 offset:4288
	v_ashrrev_i32_e32 v157, 31, v156
	v_lshlrev_b64 v[156:157], 10, v[156:157]
	v_lshl_add_u64 v[168:169], v[202:203], 0, v[156:157]
	s_and_b64 vcc, exec, s[40:41]
	v_lshl_add_u64 v[172:173], v[168:169], 2, s[52:53]
	s_cbranch_vccnz .LBB0_462
	global_load_dwordx4 v[160:163], v[172:173], off offset:16 nt
	global_load_dwordx4 v[156:159], v[172:173], off nt
	s_cbranch_execnz .LBB0_400

.LBB0_400:
	s_and_b64 vcc, exec, s[40:41]
	s_cbranch_vccnz .LBB0_463
	global_load_dwordx4 v[164:167], v[172:173], off offset:528 nt
	global_load_dwordx4 v[152:155], v[172:173], off offset:512 nt
	s_cbranch_execnz .LBB0_403

.LBB0_403:
	s_waitcnt lgkmcnt(0)
	v_pk_mul_f32 v[82:83], v[82:83], v[170:171] op_sel_hi:[1,0]
	v_pk_mul_f32 v[80:81], v[80:81], v[170:171] op_sel_hi:[1,0]
	v_pk_mul_f32 v[78:79], v[78:79], v[170:171] op_sel_hi:[1,0]
	v_pk_mul_f32 v[76:77], v[76:77], v[170:171] op_sel_hi:[1,0]
	v_pk_mul_f32 v[74:75], v[74:75], v[170:171] op_sel_hi:[1,0]
	v_pk_mul_f32 v[72:73], v[72:73], v[170:171] op_sel_hi:[1,0]
	v_pk_mul_f32 v[70:71], v[70:71], v[170:171] op_sel_hi:[1,0]
	v_pk_mul_f32 v[68:69], v[68:69], v[170:171] op_sel_hi:[1,0]
	s_waitcnt vmcnt(0)
	v_pk_fma_f32 v[82:83], v[98:99], v[82:83], v[158:159]
	v_pk_fma_f32 v[80:81], v[96:97], v[80:81], v[156:157]
	v_pk_fma_f32 v[78:79], v[94:95], v[78:79], v[162:163]
	v_pk_fma_f32 v[76:77], v[92:93], v[76:77], v[160:161]
	v_pk_fma_f32 v[74:75], v[90:91], v[74:75], v[154:155]
	v_pk_fma_f32 v[72:73], v[88:89], v[72:73], v[152:153]
	v_pk_fma_f32 v[70:71], v[86:87], v[70:71], v[166:167]
	v_pk_fma_f32 v[68:69], v[84:85], v[68:69], v[164:165]
	v_add_u32_e32 v148, 0x80, v214
	ds_read_b32 v166, v227 offset:4608
	v_ashrrev_i32_e32 v149, 31, v148
	v_lshlrev_b64 v[148:149], 10, v[148:149]
	v_lshl_add_u64 v[156:157], v[202:203], 0, v[148:149]
	s_and_b64 vcc, exec, s[40:41]
	v_lshl_add_u64 v[160:161], v[156:157], 2, s[52:53]
	s_cbranch_vccnz .LBB0_464
	global_load_dwordx4 v[148:151], v[160:161], off offset:16 nt
	global_load_dwordx4 v[152:155], v[160:161], off nt
	v_lshl_add_u64 v[164:165], v[156:157], 1, s[54:55]
	s_cbranch_execnz .LBB0_406
.LBB0_405:
	global_load_dwordx4 v[148:151], v[164:165], off nt
	s_waitcnt vmcnt(0)
	v_lshlrev_b32_e32 v152, 16, v148
	v_and_b32_e32 v153, 0xffff0000, v148
	v_lshlrev_b32_e32 v148, 16, v149
	v_and_b32_e32 v149, 0xffff0000, v149
	v_lshlrev_b32_e32 v156, 16, v150
	v_and_b32_e32 v157, 0xffff0000, v150
	v_lshlrev_b32_e32 v150, 16, v151
	v_and_b32_e32 v151, 0xffff0000, v151
	v_pk_mul_f32 v[154:155], v[210:211], v[148:149] op_sel_hi:[0,1]
	v_pk_mul_f32 v[152:153], v[210:211], v[152:153] op_sel_hi:[0,1]
	v_pk_mul_f32 v[150:151], v[210:211], v[150:151] op_sel_hi:[0,1]
	v_pk_mul_f32 v[148:149], v[210:211], v[156:157] op_sel_hi:[0,1]
.LBB0_406:
	s_and_b64 vcc, exec, s[40:41]
	s_cbranch_vccnz .LBB0_465
	global_load_dwordx4 v[156:159], v[160:161], off offset:528 nt
	s_nop 0
	global_load_dwordx4 v[160:163], v[160:161], off offset:512 nt
	s_cbranch_execnz .LBB0_409
.LBB0_408:
	global_load_dwordx4 v[156:159], v[164:165], off offset:256 nt
	s_waitcnt vmcnt(0)
	v_lshlrev_b32_e32 v160, 16, v156
	v_and_b32_e32 v161, 0xffff0000, v156
	v_lshlrev_b32_e32 v156, 16, v157
	v_and_b32_e32 v157, 0xffff0000, v157
	v_lshlrev_b32_e32 v170, 16, v158
	v_and_b32_e32 v171, 0xffff0000, v158
	v_lshlrev_b32_e32 v158, 16, v159
	v_and_b32_e32 v159, 0xffff0000, v159
	v_pk_mul_f32 v[162:163], v[210:211], v[156:157] op_sel_hi:[0,1]
	v_pk_mul_f32 v[160:161], v[210:211], v[160:161] op_sel_hi:[0,1]
	v_pk_mul_f32 v[158:159], v[210:211], v[158:159] op_sel_hi:[0,1]
	v_pk_mul_f32 v[156:157], v[210:211], v[170:171] op_sel_hi:[0,1]
.LBB0_409:
	s_waitcnt lgkmcnt(0)
	v_pk_mul_f32 v[66:67], v[66:67], v[166:167] op_sel_hi:[1,0]
	v_pk_mul_f32 v[64:65], v[64:65], v[166:167] op_sel_hi:[1,0]
	v_pk_mul_f32 v[62:63], v[62:63], v[166:167] op_sel_hi:[1,0]
	v_pk_mul_f32 v[60:61], v[60:61], v[166:167] op_sel_hi:[1,0]
	v_pk_mul_f32 v[58:59], v[58:59], v[166:167] op_sel_hi:[1,0]
	v_pk_mul_f32 v[56:57], v[56:57], v[166:167] op_sel_hi:[1,0]
	v_pk_mul_f32 v[54:55], v[54:55], v[166:167] op_sel_hi:[1,0]
	v_pk_mul_f32 v[52:53], v[52:53], v[166:167] op_sel_hi:[1,0]
	s_waitcnt vmcnt(0)
	v_pk_fma_f32 v[66:67], v[98:99], v[66:67], v[154:155]
	v_pk_fma_f32 v[64:65], v[96:97], v[64:65], v[152:153]
	v_pk_fma_f32 v[62:63], v[94:95], v[62:63], v[150:151]
	v_pk_fma_f32 v[60:61], v[92:93], v[60:61], v[148:149]
	v_pk_fma_f32 v[58:59], v[90:91], v[58:59], v[162:163]
	v_pk_fma_f32 v[56:57], v[88:89], v[56:57], v[160:161]
	v_pk_fma_f32 v[54:55], v[86:87], v[54:55], v[158:159]
	v_pk_fma_f32 v[52:53], v[84:85], v[52:53], v[156:157]
	v_add_u32_e32 v148, 0x90, v214
	ds_read_b32 v170, v227 offset:4672
	v_ashrrev_i32_e32 v149, 31, v148
	v_lshlrev_b64 v[148:149], 10, v[148:149]
	v_lshl_add_u64 v[156:157], v[202:203], 0, v[148:149]
	s_and_b64 vcc, exec, s[40:41]
	v_lshl_add_u64 v[160:161], v[156:157], 2, s[52:53]
	s_cbranch_vccnz .LBB0_466
	global_load_dwordx4 v[148:151], v[160:161], off offset:16 nt
	global_load_dwordx4 v[152:155], v[160:161], off nt
	v_lshl_add_u64 v[166:167], v[156:157], 1, s[54:55]
	s_cbranch_execnz .LBB0_412
.LBB0_411:
	global_load_dwordx4 v[148:151], v[166:167], off nt
	s_waitcnt vmcnt(0)
	v_lshlrev_b32_e32 v152, 16, v148
	v_and_b32_e32 v153, 0xffff0000, v148
	v_lshlrev_b32_e32 v148, 16, v149
	v_and_b32_e32 v149, 0xffff0000, v149
	v_lshlrev_b32_e32 v156, 16, v150
	v_and_b32_e32 v157, 0xffff0000, v150
	v_lshlrev_b32_e32 v150, 16, v151
	v_and_b32_e32 v151, 0xffff0000, v151
	v_pk_mul_f32 v[154:155], v[208:209], v[148:149] op_sel_hi:[0,1]
	v_pk_mul_f32 v[152:153], v[208:209], v[152:153] op_sel_hi:[0,1]
	v_pk_mul_f32 v[150:151], v[208:209], v[150:151] op_sel_hi:[0,1]
	v_pk_mul_f32 v[148:149], v[208:209], v[156:157] op_sel_hi:[0,1]

.LBB0_414:
	global_load_dwordx4 v[156:159], v[166:167], off offset:256 nt
	s_waitcnt vmcnt(0)
	v_lshlrev_b32_e32 v160, 16, v156
	v_and_b32_e32 v161, 0xffff0000, v156
	v_lshlrev_b32_e32 v156, 16, v157
	v_and_b32_e32 v157, 0xffff0000, v157
	v_lshlrev_b32_e32 v172, 16, v158
	v_and_b32_e32 v173, 0xffff0000, v158
	v_lshlrev_b32_e32 v158, 16, v159
	v_and_b32_e32 v159, 0xffff0000, v159
	v_pk_mul_f32 v[162:163], v[208:209], v[156:157] op_sel_hi:[0,1]
	v_pk_mul_f32 v[160:161], v[208:209], v[160:161] op_sel_hi:[0,1]
	v_pk_mul_f32 v[158:159], v[208:209], v[158:159] op_sel_hi:[0,1]
	v_pk_mul_f32 v[156:157], v[208:209], v[172:173] op_sel_hi:[0,1]
.LBB0_415:
	s_waitcnt lgkmcnt(0)
	v_pk_mul_f32 v[50:51], v[50:51], v[170:171] op_sel_hi:[1,0]
	v_pk_mul_f32 v[48:49], v[48:49], v[170:171] op_sel_hi:[1,0]
	v_pk_mul_f32 v[46:47], v[46:47], v[170:171] op_sel_hi:[1,0]
	v_pk_mul_f32 v[44:45], v[44:45], v[170:171] op_sel_hi:[1,0]
	v_pk_mul_f32 v[42:43], v[42:43], v[170:171] op_sel_hi:[1,0]
	v_pk_mul_f32 v[40:41], v[40:41], v[170:171] op_sel_hi:[1,0]
	v_pk_mul_f32 v[38:39], v[38:39], v[170:171] op_sel_hi:[1,0]
	v_pk_mul_f32 v[36:37], v[36:37], v[170:171] op_sel_hi:[1,0]
	s_waitcnt vmcnt(0)
	v_pk_fma_f32 v[50:51], v[98:99], v[50:51], v[154:155]
	v_pk_fma_f32 v[48:49], v[96:97], v[48:49], v[152:153]
	v_pk_fma_f32 v[46:47], v[94:95], v[46:47], v[150:151]
	v_pk_fma_f32 v[44:45], v[92:93], v[44:45], v[148:149]
	v_pk_fma_f32 v[42:43], v[90:91], v[42:43], v[162:163]
	v_pk_fma_f32 v[40:41], v[88:89], v[40:41], v[160:161]
	v_pk_fma_f32 v[38:39], v[86:87], v[38:39], v[158:159]
	v_pk_fma_f32 v[36:37], v[84:85], v[36:37], v[156:157]
	v_add_u32_e32 v148, 0xa0, v214
	ds_read_b32 v172, v227 offset:4736
	v_ashrrev_i32_e32 v149, 31, v148
	v_lshlrev_b64 v[148:149], 10, v[148:149]
	v_lshl_add_u64 v[156:157], v[202:203], 0, v[148:149]
	s_and_b64 vcc, exec, s[40:41]
	v_lshl_add_u64 v[160:161], v[156:157], 2, s[52:53]
	s_cbranch_vccnz .LBB0_468
	global_load_dwordx4 v[148:151], v[160:161], off offset:16 nt
	global_load_dwordx4 v[152:155], v[160:161], off nt
	v_lshl_add_u64 v[170:171], v[156:157], 1, s[54:55]
	s_cbranch_execnz .LBB0_418
.LBB0_417:
	global_load_dwordx4 v[148:151], v[170:171], off nt
	s_waitcnt vmcnt(0)
	v_lshlrev_b32_e32 v152, 16, v148
	v_and_b32_e32 v153, 0xffff0000, v148
	v_lshlrev_b32_e32 v148, 16, v149
	v_and_b32_e32 v149, 0xffff0000, v149
	v_lshlrev_b32_e32 v156, 16, v150
	v_and_b32_e32 v157, 0xffff0000, v150
	v_lshlrev_b32_e32 v150, 16, v151
	v_and_b32_e32 v151, 0xffff0000, v151
	v_pk_mul_f32 v[154:155], v[2:3], v[148:149] op_sel_hi:[0,1]
	v_pk_mul_f32 v[152:153], v[2:3], v[152:153] op_sel_hi:[0,1]
	v_pk_mul_f32 v[150:151], v[2:3], v[150:151] op_sel_hi:[0,1]
	v_pk_mul_f32 v[148:149], v[2:3], v[156:157] op_sel_hi:[0,1]

.LBB0_420:
	global_load_dwordx4 v[156:159], v[170:171], off offset:256 nt
	s_waitcnt vmcnt(0)
	v_lshlrev_b32_e32 v160, 16, v156
	v_and_b32_e32 v161, 0xffff0000, v156
	v_lshlrev_b32_e32 v156, 16, v157
	v_and_b32_e32 v157, 0xffff0000, v157
	v_lshlrev_b32_e32 v174, 16, v158
	v_and_b32_e32 v175, 0xffff0000, v158
	v_lshlrev_b32_e32 v158, 16, v159
	v_and_b32_e32 v159, 0xffff0000, v159
	v_pk_mul_f32 v[162:163], v[2:3], v[156:157] op_sel_hi:[0,1]
	v_pk_mul_f32 v[160:161], v[2:3], v[160:161] op_sel_hi:[0,1]
	v_pk_mul_f32 v[158:159], v[2:3], v[158:159] op_sel_hi:[0,1]
	v_pk_mul_f32 v[156:157], v[2:3], v[174:175] op_sel_hi:[0,1]
.LBB0_421:
	s_waitcnt lgkmcnt(0)
	v_pk_mul_f32 v[34:35], v[34:35], v[172:173] op_sel_hi:[1,0]
	v_pk_mul_f32 v[32:33], v[32:33], v[172:173] op_sel_hi:[1,0]
	v_pk_mul_f32 v[30:31], v[30:31], v[172:173] op_sel_hi:[1,0]
	v_pk_mul_f32 v[28:29], v[28:29], v[172:173] op_sel_hi:[1,0]
	v_pk_mul_f32 v[26:27], v[26:27], v[172:173] op_sel_hi:[1,0]
	v_pk_mul_f32 v[24:25], v[24:25], v[172:173] op_sel_hi:[1,0]
	v_pk_mul_f32 v[22:23], v[22:23], v[172:173] op_sel_hi:[1,0]
	v_pk_mul_f32 v[20:21], v[20:21], v[172:173] op_sel_hi:[1,0]
	s_waitcnt vmcnt(0)
	v_pk_fma_f32 v[34:35], v[98:99], v[34:35], v[154:155]
	v_pk_fma_f32 v[32:33], v[96:97], v[32:33], v[152:153]
	v_pk_fma_f32 v[30:31], v[94:95], v[30:31], v[150:151]
	v_pk_fma_f32 v[28:29], v[92:93], v[28:29], v[148:149]
	v_pk_fma_f32 v[26:27], v[90:91], v[26:27], v[162:163]
	v_pk_fma_f32 v[24:25], v[88:89], v[24:25], v[160:161]
	v_pk_fma_f32 v[22:23], v[86:87], v[22:23], v[158:159]
	v_pk_fma_f32 v[20:21], v[84:85], v[20:21], v[156:157]
	v_add_u32_e32 v148, 0xb0, v214
	ds_read_b32 v2, v227 offset:4800
	v_ashrrev_i32_e32 v149, 31, v148
	v_lshlrev_b64 v[148:149], 10, v[148:149]
	v_lshl_add_u64 v[148:149], v[202:203], 0, v[148:149]
	s_and_b64 vcc, exec, s[40:41]
	v_lshl_add_u64 v[152:153], v[148:149], 2, s[52:53]
	s_cbranch_vccnz .LBB0_470
	global_load_dwordx4 v[156:159], v[152:153], off offset:16 nt
	global_load_dwordx4 v[160:163], v[152:153], off nt
	v_lshl_add_u64 v[172:173], v[148:149], 1, s[54:55]
	s_cbranch_execnz .LBB0_424
.LBB0_423:
	global_load_dwordx4 v[148:151], v[172:173], off nt
	s_waitcnt vmcnt(0)
	v_lshlrev_b32_e32 v154, 16, v148
	v_and_b32_e32 v155, 0xffff0000, v148
	v_lshlrev_b32_e32 v148, 16, v149
	v_and_b32_e32 v149, 0xffff0000, v149
	v_lshlrev_b32_e32 v156, 16, v150
	v_and_b32_e32 v157, 0xffff0000, v150
	v_lshlrev_b32_e32 v150, 16, v151
	v_and_b32_e32 v151, 0xffff0000, v151
	v_pk_mul_f32 v[162:163], v[0:1], v[148:149] op_sel_hi:[0,1]
	v_pk_mul_f32 v[160:161], v[0:1], v[154:155] op_sel_hi:[0,1]
	v_pk_mul_f32 v[158:159], v[0:1], v[150:151] op_sel_hi:[0,1]
	v_pk_mul_f32 v[156:157], v[0:1], v[156:157] op_sel_hi:[0,1]
.LBB0_424:
	s_and_b64 vcc, exec, s[40:41]
	s_cbranch_vccnz .LBB0_471
	global_load_dwordx4 v[148:151], v[152:153], off offset:528 nt
	s_nop 0
	global_load_dwordx4 v[152:155], v[152:153], off offset:512 nt
	s_cbranch_execnz .LBB0_427
.LBB0_426:
	global_load_dwordx4 v[148:151], v[172:173], off offset:256 nt
	s_waitcnt vmcnt(0)
	v_lshlrev_b32_e32 v152, 16, v148
	v_and_b32_e32 v153, 0xffff0000, v148
	v_lshlrev_b32_e32 v148, 16, v149
	v_and_b32_e32 v149, 0xffff0000, v149
	v_lshlrev_b32_e32 v174, 16, v150
	v_and_b32_e32 v175, 0xffff0000, v150
	v_lshlrev_b32_e32 v150, 16, v151
	v_and_b32_e32 v151, 0xffff0000, v151
	v_pk_mul_f32 v[154:155], v[0:1], v[148:149] op_sel_hi:[0,1]
	v_pk_mul_f32 v[152:153], v[0:1], v[152:153] op_sel_hi:[0,1]
	v_pk_mul_f32 v[150:151], v[0:1], v[150:151] op_sel_hi:[0,1]
	v_pk_mul_f32 v[148:149], v[0:1], v[174:175] op_sel_hi:[0,1]

.LBB0_608:
	s_add_u32 s0, s18, s6
	s_addc_u32 s1, s29, s7
	s_add_u32 s6, s46, 0x1ea00000
	s_addc_u32 s7, s47, 0
	s_lshl_b32 s8, s36, 5
	s_lshl_b32 s9, s40, 8
	v_lshrrev_b32_e32 v0, 1, v190
	s_or_b32 s8, s9, s8
	v_and_or_b32 v0, v0, 24, s8
	s_lshl_b32 s8, s25, 8
	s_or_b32 s9, s8, 0x80
	v_ashrrev_i32_e32 v1, 31, v0
	v_add_u32_e32 v188, s8, v205
	v_add_u32_e32 v130, s9, v205
	v_lshl_add_u64 v[128:129], v[0:1], 1, s[46:47]
	s_mov_b64 s[10:11], 0x3600000
	v_ashrrev_i32_e32 v189, 31, v188
	v_ashrrev_i32_e32 v131, 31, v130
	v_lshl_add_u64 v[180:181], v[128:129], 0, s[10:11]
	v_lshl_add_u64 v[128:129], v[188:189], 2, s[6:7]
	v_lshl_add_u64 v[130:131], v[130:131], 2, s[6:7]
	v_lshlrev_b64 v[132:133], 11, v[188:189]
	v_or_b32_e32 v2, 16, v205
	s_barrier
	v_lshl_add_u64 v[132:133], v[180:181], 0, v[132:133]
	global_load_dword v214, v[128:129], off
	global_load_dword v206, v[130:131], off
	global_load_dwordx4 v[176:179], v[132:133], off nt
	v_add_u32_e32 v186, s8, v2
	v_add_u32_e32 v130, s9, v2
	v_ashrrev_i32_e32 v187, 31, v186
	v_ashrrev_i32_e32 v131, 31, v130
	v_lshl_add_u64 v[128:129], v[186:187], 2, s[6:7]
	v_lshl_add_u64 v[130:131], v[130:131], 2, s[6:7]
	v_or_b32_e32 v2, 32, v205
	global_load_dwordx4 v[172:175], v[132:133], off offset:256 nt
	global_load_dword v212, v[128:129], off
	global_load_dword v204, v[130:131], off
	v_lshlrev_b64 v[128:129], 11, v[186:187]
	v_add_u32_e32 v184, s8, v2
	v_add_u32_e32 v130, s9, v2
	v_lshl_add_u64 v[128:129], v[180:181], 0, v[128:129]
	v_ashrrev_i32_e32 v185, 31, v184
	v_ashrrev_i32_e32 v131, 31, v130
	v_or_b32_e32 v2, 48, v205
	global_load_dwordx4 v[168:171], v[128:129], off nt
	global_load_dwordx4 v[164:167], v[128:129], off offset:256 nt
	v_lshl_add_u64 v[128:129], v[184:185], 2, s[6:7]
	v_lshl_add_u64 v[130:131], v[130:131], 2, s[6:7]
	v_lshlrev_b64 v[132:133], 11, v[184:185]
	v_add_u32_e32 v182, s8, v2
	v_lshl_add_u64 v[132:133], v[180:181], 0, v[132:133]
	global_load_dword v210, v[128:129], off
	global_load_dword v202, v[130:131], off
	global_load_dwordx4 v[160:163], v[132:133], off nt
	v_ashrrev_i32_e32 v183, 31, v182
	v_add_u32_e32 v130, s9, v2
	v_lshl_add_u64 v[128:129], v[182:183], 2, s[6:7]
	v_ashrrev_i32_e32 v131, 31, v130
	v_lshl_add_u64 v[130:131], v[130:131], 2, s[6:7]
	global_load_dwordx4 v[156:159], v[132:133], off offset:256 nt
	global_load_dword v208, v[128:129], off
	global_load_dword v2, v[130:131], off
	v_lshlrev_b64 v[128:129], 11, v[182:183]
	v_lshl_add_u64 v[128:129], v[180:181], 0, v[128:129]
	global_load_dwordx4 v[152:155], v[128:129], off nt
	global_load_dwordx4 v[148:151], v[128:129], off offset:256 nt
	v_lshl_add_u64 v[128:129], v[0:1], 2, s[0:1]
	s_mov_b64 s[0:1], 0x3000
	v_lshl_add_u64 v[132:133], v[128:129], 0, s[0:1]
	s_movk_i32 s0, 0x3000
	v_add_co_u32_e32 v128, vcc, s0, v128
	v_and_b32_e32 v203, 64, v226
	s_nop 0
	v_addc_co_u32_e32 v129, vcc, 0, v129, vcc
	global_load_dwordx4 v[136:139], v[128:129], off nt
	s_nop 0
	global_load_dwordx4 v[128:131], v[132:133], off offset:528 nt
	global_load_dwordx4 v[140:143], v[132:133], off offset:16 nt
	s_nop 0
	global_load_dwordx4 v[132:135], v[132:133], off offset:512 nt
	v_xor_b32_e32 v191, 16, v226
	v_add_u32_e32 v203, 64, v203
	v_cmp_lt_i32_e32 vcc, v191, v203
	v_mul_f32_e32 v215, v147, v147
	v_fmac_f32_e32 v215, v146, v146
	v_cndmask_b32_e32 v191, v226, v191, vcc
	v_lshlrev_b32_e32 v207, 2, v191
	v_mul_f32_e32 v191, v145, v145
	v_fmac_f32_e32 v191, v144, v144
	v_add_f32_e32 v191, v191, v215
	v_mul_f32_e32 v215, v125, v125
	v_mul_f32_e32 v216, v127, v127
	v_fmac_f32_e32 v215, v124, v124
	v_fmac_f32_e32 v216, v126, v126
	v_add_f32_e32 v215, v215, v216
	v_add_f32_e32 v191, v191, v215
	v_mul_f32_e32 v215, v121, v121
	v_mul_f32_e32 v216, v123, v123
	v_fmac_f32_e32 v215, v120, v120
	v_fmac_f32_e32 v216, v122, v122
	v_add_f32_e32 v215, v215, v216
	v_add_f32_e32 v191, v191, v215
	v_mul_f32_e32 v215, v117, v117
	v_mul_f32_e32 v216, v119, v119
	v_fmac_f32_e32 v215, v116, v116
	v_fmac_f32_e32 v216, v118, v118
	v_add_f32_e32 v215, v215, v216
	v_add_f32_e32 v191, v191, v215
	v_mov_b32_e32 v216, v191
	s_nop 1
	v_permlane16_swap_b32_e32 v216, v191
	v_xor_b32_e32 v215, 32, v226
	v_cmp_lt_i32_e32 vcc, v215, v203
	s_lshl_b32 s0, s36, 2
	s_add_i32 s10, s0, 0
	v_cndmask_b32_e32 v203, v226, v215, vcc
	v_lshlrev_b32_e32 v215, 2, v203
	s_waitcnt lgkmcnt(0)
	v_add_f32_e32 v191, v191, v216
	v_mov_b32_e32 v216, v191
	s_nop 1
	v_permlane32_swap_b32_e32 v216, v191
	v_and_b32_e32 v203, 63, v190
	v_cmp_gt_u32_e64 s[38:39], 16, v203
	s_and_saveexec_b64 s[0:1], s[38:39]
	s_cbranch_execz .LBB0_610
	s_lshl_b32 s6, s20, 10
	s_add_i32 s6, s10, s6
	v_lshl_add_u32 v217, v193, 4, s6
	s_waitcnt lgkmcnt(0)
	v_add_f32_e32 v191, v191, v216
	ds_write_b32 v217, v191

.LBB0_634:
	s_or_b64 exec, exec, s[0:1]
	s_waitcnt lgkmcnt(0)
	s_barrier
	v_lshl_add_u32 v205, v205, 2, 0
	ds_read_b32 v216, v205 offset:4096
	s_waitcnt vmcnt(0)
	v_lshlrev_b32_e32 v224, 16, v176
	v_and_b32_e32 v225, 0xffff0000, v176
	v_lshlrev_b32_e32 v176, 16, v177
	v_and_b32_e32 v177, 0xffff0000, v177
	s_waitcnt lgkmcnt(0)
	v_pk_mul_f32 v[146:147], v[146:147], v[216:217] op_sel_hi:[1,0]
	v_pk_mul_f32 v[126:127], v[126:127], v[216:217] op_sel_hi:[1,0]
	v_lshlrev_b32_e32 v228, 16, v178
	v_and_b32_e32 v229, 0xffff0000, v178
	v_lshlrev_b32_e32 v178, 16, v179
	v_and_b32_e32 v179, 0xffff0000, v179
	v_pk_mul_f32 v[144:145], v[144:145], v[216:217] op_sel_hi:[1,0]
	v_pk_mul_f32 v[146:147], v[138:139], v[146:147]
	v_pk_mul_f32 v[124:125], v[124:125], v[216:217] op_sel_hi:[1,0]
	v_pk_mul_f32 v[126:127], v[142:143], v[126:127]
	v_pk_mul_f32 v[122:123], v[122:123], v[216:217] op_sel_hi:[1,0]
	v_pk_mul_f32 v[120:121], v[120:121], v[216:217] op_sel_hi:[1,0]
	v_pk_mul_f32 v[118:119], v[118:119], v[216:217] op_sel_hi:[1,0]
	v_pk_mul_f32 v[116:117], v[116:117], v[216:217] op_sel_hi:[1,0]
	v_pk_mul_f32 v[144:145], v[136:137], v[144:145]
	v_pk_fma_f32 v[146:147], v[214:215], v[176:177], v[146:147] op_sel_hi:[0,1,1]
	v_pk_mul_f32 v[124:125], v[140:141], v[124:125]
	v_pk_fma_f32 v[126:127], v[214:215], v[178:179], v[126:127] op_sel_hi:[0,1,1]
	v_lshlrev_b32_e32 v176, 16, v172
	v_and_b32_e32 v177, 0xffff0000, v172
	v_lshlrev_b32_e32 v172, 16, v173
	v_and_b32_e32 v173, 0xffff0000, v173
	v_lshlrev_b32_e32 v178, 16, v174
	v_and_b32_e32 v179, 0xffff0000, v174
	v_lshlrev_b32_e32 v174, 16, v175
	v_and_b32_e32 v175, 0xffff0000, v175
	v_pk_mul_f32 v[120:121], v[132:133], v[120:121]
	v_pk_mul_f32 v[122:123], v[134:135], v[122:123]
	v_pk_mul_f32 v[116:117], v[128:129], v[116:117]
	v_pk_mul_f32 v[118:119], v[130:131], v[118:119]
	v_pk_fma_f32 v[144:145], v[214:215], v[224:225], v[144:145] op_sel_hi:[0,1,1]
	v_pk_fma_f32 v[124:125], v[214:215], v[228:229], v[124:125] op_sel_hi:[0,1,1]
	v_pk_fma_f32 v[122:123], v[214:215], v[172:173], v[122:123] op_sel_hi:[0,1,1]
	v_pk_fma_f32 v[120:121], v[214:215], v[176:177], v[120:121] op_sel_hi:[0,1,1]
	v_pk_fma_f32 v[118:119], v[214:215], v[174:175], v[118:119] op_sel_hi:[0,1,1]
	v_pk_fma_f32 v[116:117], v[214:215], v[178:179], v[116:117] op_sel_hi:[0,1,1]
	ds_read_b32 v172, v205 offset:4160
	v_lshlrev_b32_e32 v174, 16, v168
	v_and_b32_e32 v175, 0xffff0000, v168
	v_lshlrev_b32_e32 v168, 16, v169
	v_and_b32_e32 v169, 0xffff0000, v169
	s_waitcnt lgkmcnt(0)
	v_pk_mul_f32 v[114:115], v[114:115], v[172:173] op_sel_hi:[1,0]
	v_pk_mul_f32 v[110:111], v[110:111], v[172:173] op_sel_hi:[1,0]
	v_lshlrev_b32_e32 v176, 16, v170
	v_and_b32_e32 v177, 0xffff0000, v170
	v_lshlrev_b32_e32 v170, 16, v171
	v_and_b32_e32 v171, 0xffff0000, v171
	v_pk_mul_f32 v[112:113], v[112:113], v[172:173] op_sel_hi:[1,0]
	v_pk_mul_f32 v[114:115], v[138:139], v[114:115]
	v_pk_mul_f32 v[108:109], v[108:109], v[172:173] op_sel_hi:[1,0]
	v_pk_mul_f32 v[110:111], v[142:143], v[110:111]
	v_pk_mul_f32 v[106:107], v[106:107], v[172:173] op_sel_hi:[1,0]
	v_pk_mul_f32 v[104:105], v[104:105], v[172:173] op_sel_hi:[1,0]
	v_pk_mul_f32 v[102:103], v[102:103], v[172:173] op_sel_hi:[1,0]
	v_pk_mul_f32 v[100:101], v[100:101], v[172:173] op_sel_hi:[1,0]
	v_pk_mul_f32 v[112:113], v[136:137], v[112:113]
	v_pk_fma_f32 v[114:115], v[212:213], v[168:169], v[114:115] op_sel_hi:[0,1,1]
	v_pk_mul_f32 v[108:109], v[140:141], v[108:109]
	v_pk_fma_f32 v[110:111], v[212:213], v[170:171], v[110:111] op_sel_hi:[0,1,1]
	v_lshlrev_b32_e32 v168, 16, v164
	v_and_b32_e32 v169, 0xffff0000, v164
	v_lshlrev_b32_e32 v164, 16, v165
	v_and_b32_e32 v165, 0xffff0000, v165
	v_lshlrev_b32_e32 v170, 16, v166
	v_and_b32_e32 v171, 0xffff0000, v166
	v_lshlrev_b32_e32 v166, 16, v167
	v_and_b32_e32 v167, 0xffff0000, v167
	v_pk_mul_f32 v[104:105], v[132:133], v[104:105]
	v_pk_mul_f32 v[106:107], v[134:135], v[106:107]
	v_pk_mul_f32 v[100:101], v[128:129], v[100:101]
	v_pk_mul_f32 v[102:103], v[130:131], v[102:103]
	v_pk_fma_f32 v[112:113], v[212:213], v[174:175], v[112:113] op_sel_hi:[0,1,1]
	v_pk_fma_f32 v[108:109], v[212:213], v[176:177], v[108:109] op_sel_hi:[0,1,1]
	v_pk_fma_f32 v[106:107], v[212:213], v[164:165], v[106:107] op_sel_hi:[0,1,1]
	v_pk_fma_f32 v[104:105], v[212:213], v[168:169], v[104:105] op_sel_hi:[0,1,1]
	v_pk_fma_f32 v[102:103], v[212:213], v[166:167], v[102:103] op_sel_hi:[0,1,1]
	v_pk_fma_f32 v[100:101], v[212:213], v[170:171], v[100:101] op_sel_hi:[0,1,1]
	ds_read_b32 v164, v205 offset:4224
	v_lshlrev_b32_e32 v166, 16, v160
	v_and_b32_e32 v167, 0xffff0000, v160
	v_lshlrev_b32_e32 v160, 16, v161
	v_and_b32_e32 v161, 0xffff0000, v161
	s_waitcnt lgkmcnt(0)
	v_pk_mul_f32 v[98:99], v[98:99], v[164:165] op_sel_hi:[1,0]
	v_pk_mul_f32 v[94:95], v[94:95], v[164:165] op_sel_hi:[1,0]
	v_lshlrev_b32_e32 v168, 16, v162
	v_and_b32_e32 v169, 0xffff0000, v162
	v_lshlrev_b32_e32 v162, 16, v163
	v_and_b32_e32 v163, 0xffff0000, v163
	v_pk_mul_f32 v[96:97], v[96:97], v[164:165] op_sel_hi:[1,0]
	v_pk_mul_f32 v[98:99], v[138:139], v[98:99]
	v_pk_mul_f32 v[92:93], v[92:93], v[164:165] op_sel_hi:[1,0]
	v_pk_mul_f32 v[94:95], v[142:143], v[94:95]
	v_pk_mul_f32 v[90:91], v[90:91], v[164:165] op_sel_hi:[1,0]
	v_pk_mul_f32 v[88:89], v[88:89], v[164:165] op_sel_hi:[1,0]
	v_pk_mul_f32 v[86:87], v[86:87], v[164:165] op_sel_hi:[1,0]
	v_pk_mul_f32 v[84:85], v[84:85], v[164:165] op_sel_hi:[1,0]
	v_pk_mul_f32 v[96:97], v[136:137], v[96:97]
	v_pk_fma_f32 v[98:99], v[210:211], v[160:161], v[98:99] op_sel_hi:[0,1,1]
	v_pk_mul_f32 v[92:93], v[140:141], v[92:93]
	v_pk_fma_f32 v[94:95], v[210:211], v[162:163], v[94:95] op_sel_hi:[0,1,1]
	v_lshlrev_b32_e32 v160, 16, v156
	v_and_b32_e32 v161, 0xffff0000, v156
	v_lshlrev_b32_e32 v156, 16, v157
	v_and_b32_e32 v157, 0xffff0000, v157
	v_lshlrev_b32_e32 v162, 16, v158
	v_and_b32_e32 v163, 0xffff0000, v158
	v_lshlrev_b32_e32 v158, 16, v159
	v_and_b32_e32 v159, 0xffff0000, v159
	v_pk_mul_f32 v[88:89], v[132:133], v[88:89]
	v_pk_mul_f32 v[90:91], v[134:135], v[90:91]
	v_pk_mul_f32 v[84:85], v[128:129], v[84:85]
	v_pk_mul_f32 v[86:87], v[130:131], v[86:87]
	v_pk_fma_f32 v[96:97], v[210:211], v[166:167], v[96:97] op_sel_hi:[0,1,1]
	v_pk_fma_f32 v[92:93], v[210:211], v[168:169], v[92:93] op_sel_hi:[0,1,1]
	v_pk_fma_f32 v[90:91], v[210:211], v[156:157], v[90:91] op_sel_hi:[0,1,1]
	v_pk_fma_f32 v[88:89], v[210:211], v[160:161], v[88:89] op_sel_hi:[0,1,1]
	v_pk_fma_f32 v[86:87], v[210:211], v[158:159], v[86:87] op_sel_hi:[0,1,1]
	v_pk_fma_f32 v[84:85], v[210:211], v[162:163], v[84:85] op_sel_hi:[0,1,1]
	ds_read_b32 v156, v205 offset:4288
	v_lshlrev_b32_e32 v158, 16, v152
	v_and_b32_e32 v159, 0xffff0000, v152
	v_lshlrev_b32_e32 v152, 16, v153
	v_and_b32_e32 v153, 0xffff0000, v153
	s_waitcnt lgkmcnt(0)
	v_pk_mul_f32 v[82:83], v[82:83], v[156:157] op_sel_hi:[1,0]
	v_pk_mul_f32 v[72:73], v[72:73], v[156:157] op_sel_hi:[1,0]
	v_pk_mul_f32 v[82:83], v[138:139], v[82:83]
	v_pk_mul_f32 v[72:73], v[132:133], v[72:73]
	v_pk_fma_f32 v[82:83], v[208:209], v[152:153], v[82:83] op_sel_hi:[0,1,1]
	v_lshlrev_b32_e32 v152, 16, v148
	v_and_b32_e32 v153, 0xffff0000, v148
	v_pk_mul_f32 v[78:79], v[78:79], v[156:157] op_sel_hi:[1,0]
	v_pk_mul_f32 v[74:75], v[74:75], v[156:157] op_sel_hi:[1,0]
	v_pk_fma_f32 v[72:73], v[208:209], v[152:153], v[72:73] op_sel_hi:[0,1,1]
	v_add_u32_e32 v152, 0x80, v188
	v_lshlrev_b32_e32 v160, 16, v154
	v_and_b32_e32 v161, 0xffff0000, v154
	v_lshlrev_b32_e32 v154, 16, v155
	v_and_b32_e32 v155, 0xffff0000, v155
	v_pk_mul_f32 v[80:81], v[80:81], v[156:157] op_sel_hi:[1,0]
	v_pk_mul_f32 v[76:77], v[76:77], v[156:157] op_sel_hi:[1,0]
	v_pk_mul_f32 v[78:79], v[142:143], v[78:79]
	v_lshlrev_b32_e32 v148, 16, v149
	v_and_b32_e32 v149, 0xffff0000, v149
	v_pk_mul_f32 v[74:75], v[134:135], v[74:75]
	v_pk_mul_f32 v[70:71], v[70:71], v[156:157] op_sel_hi:[1,0]
	v_pk_mul_f32 v[68:69], v[68:69], v[156:157] op_sel_hi:[1,0]
	v_ashrrev_i32_e32 v153, 31, v152
	v_pk_mul_f32 v[80:81], v[136:137], v[80:81]
	v_pk_mul_f32 v[76:77], v[140:141], v[76:77]
	v_pk_fma_f32 v[78:79], v[208:209], v[154:155], v[78:79] op_sel_hi:[0,1,1]
	v_lshlrev_b32_e32 v154, 16, v150
	v_and_b32_e32 v155, 0xffff0000, v150
	v_lshlrev_b32_e32 v150, 16, v151
	v_and_b32_e32 v151, 0xffff0000, v151
	v_pk_fma_f32 v[74:75], v[208:209], v[148:149], v[74:75] op_sel_hi:[0,1,1]
	v_pk_mul_f32 v[68:69], v[128:129], v[68:69]
	v_pk_mul_f32 v[70:71], v[130:131], v[70:71]
	v_lshlrev_b64 v[148:149], 11, v[152:153]
	v_pk_fma_f32 v[80:81], v[208:209], v[158:159], v[80:81] op_sel_hi:[0,1,1]
	v_pk_fma_f32 v[76:77], v[208:209], v[160:161], v[76:77] op_sel_hi:[0,1,1]
	v_pk_fma_f32 v[70:71], v[208:209], v[150:151], v[70:71] op_sel_hi:[0,1,1]
	v_pk_fma_f32 v[68:69], v[208:209], v[154:155], v[68:69] op_sel_hi:[0,1,1]
	v_lshl_add_u64 v[148:149], v[180:181], 0, v[148:149]
	global_load_dwordx4 v[154:157], v[148:149], off nt
	global_load_dwordx4 v[158:161], v[148:149], off offset:256 nt
	ds_read_b32 v150, v205 offset:4608
	s_add_u32 s4, s94, s4
	s_addc_u32 s5, s95, s5
	s_mov_b64 s[0:1], -1
	s_and_b64 vcc, exec, s[44:45]
	s_waitcnt lgkmcnt(0)
	v_pk_mul_f32 v[62:63], v[62:63], v[150:151] op_sel_hi:[1,0]
	v_pk_mul_f32 v[58:59], v[58:59], v[150:151] op_sel_hi:[1,0]
	v_pk_mul_f32 v[66:67], v[66:67], v[150:151] op_sel_hi:[1,0]
	v_pk_mul_f32 v[64:65], v[64:65], v[150:151] op_sel_hi:[1,0]
	v_pk_mul_f32 v[60:61], v[60:61], v[150:151] op_sel_hi:[1,0]
	v_pk_mul_f32 v[56:57], v[56:57], v[150:151] op_sel_hi:[1,0]
	v_pk_mul_f32 v[52:53], v[52:53], v[150:151] op_sel_hi:[1,0]
	v_pk_mul_f32 v[54:55], v[54:55], v[150:151] op_sel_hi:[1,0]
	s_waitcnt vmcnt(1)
	v_lshlrev_b32_e32 v164, 16, v156
	v_and_b32_e32 v165, 0xffff0000, v156
	v_lshlrev_b32_e32 v156, 16, v157
	v_and_b32_e32 v157, 0xffff0000, v157
	v_pk_mul_f32 v[156:157], v[206:207], v[156:157] op_sel_hi:[0,1]
	v_pk_fma_f32 v[62:63], v[142:143], v[62:63], v[156:157]
	s_waitcnt vmcnt(0)
	v_lshlrev_b32_e32 v156, 16, v159
	v_and_b32_e32 v157, 0xffff0000, v159
	v_lshlrev_b32_e32 v162, 16, v154
	v_and_b32_e32 v163, 0xffff0000, v154
	v_lshlrev_b32_e32 v154, 16, v155
	v_and_b32_e32 v155, 0xffff0000, v155
	v_pk_mul_f32 v[156:157], v[206:207], v[156:157] op_sel_hi:[0,1]
	v_pk_mul_f32 v[154:155], v[206:207], v[154:155] op_sel_hi:[0,1]
	v_pk_fma_f32 v[58:59], v[134:135], v[58:59], v[156:157]
	v_add_u32_e32 v156, 0x90, v188
	v_pk_fma_f32 v[66:67], v[138:139], v[66:67], v[154:155]
	v_lshlrev_b32_e32 v154, 16, v158
	v_and_b32_e32 v155, 0xffff0000, v158
	v_lshlrev_b32_e32 v158, 16, v160
	v_and_b32_e32 v159, 0xffff0000, v160
	v_lshlrev_b32_e32 v160, 16, v161
	v_and_b32_e32 v161, 0xffff0000, v161
	v_ashrrev_i32_e32 v157, 31, v156
	v_pk_mul_f32 v[162:163], v[206:207], v[162:163] op_sel_hi:[0,1]
	v_pk_mul_f32 v[164:165], v[206:207], v[164:165] op_sel_hi:[0,1]
	v_pk_mul_f32 v[154:155], v[206:207], v[154:155] op_sel_hi:[0,1]
	v_pk_mul_f32 v[158:159], v[206:207], v[158:159] op_sel_hi:[0,1]
	v_pk_mul_f32 v[160:161], v[206:207], v[160:161] op_sel_hi:[0,1]
	v_lshlrev_b64 v[150:151], 11, v[156:157]
	v_pk_fma_f32 v[64:65], v[136:137], v[64:65], v[162:163]
	v_pk_fma_f32 v[60:61], v[140:141], v[60:61], v[164:165]
	v_pk_fma_f32 v[56:57], v[132:133], v[56:57], v[154:155]
	v_pk_fma_f32 v[54:55], v[130:131], v[54:55], v[160:161]
	v_pk_fma_f32 v[52:53], v[128:129], v[52:53], v[158:159]
	v_lshl_add_u64 v[150:151], v[180:181], 0, v[150:151]
	global_load_dwordx4 v[158:161], v[150:151], off nt
	global_load_dwordx4 v[162:165], v[150:151], off offset:256 nt
	ds_read_b32 v154, v205 offset:4672
	s_waitcnt lgkmcnt(0)
	v_pk_mul_f32 v[46:47], v[46:47], v[154:155] op_sel_hi:[1,0]
	v_pk_mul_f32 v[42:43], v[42:43], v[154:155] op_sel_hi:[1,0]
	v_pk_mul_f32 v[50:51], v[50:51], v[154:155] op_sel_hi:[1,0]
	v_pk_mul_f32 v[48:49], v[48:49], v[154:155] op_sel_hi:[1,0]
	v_pk_mul_f32 v[44:45], v[44:45], v[154:155] op_sel_hi:[1,0]
	v_pk_mul_f32 v[40:41], v[40:41], v[154:155] op_sel_hi:[1,0]
	v_pk_mul_f32 v[36:37], v[36:37], v[154:155] op_sel_hi:[1,0]
	v_pk_mul_f32 v[38:39], v[38:39], v[154:155] op_sel_hi:[1,0]
	s_waitcnt vmcnt(1)
	v_lshlrev_b32_e32 v168, 16, v160
	v_and_b32_e32 v169, 0xffff0000, v160
	v_lshlrev_b32_e32 v160, 16, v161
	v_and_b32_e32 v161, 0xffff0000, v161
	v_pk_mul_f32 v[160:161], v[204:205], v[160:161] op_sel_hi:[0,1]
	v_pk_fma_f32 v[46:47], v[142:143], v[46:47], v[160:161]
	s_waitcnt vmcnt(0)
	v_lshlrev_b32_e32 v160, 16, v163
	v_and_b32_e32 v161, 0xffff0000, v163
	v_lshlrev_b32_e32 v166, 16, v158
	v_and_b32_e32 v167, 0xffff0000, v158
	v_lshlrev_b32_e32 v158, 16, v159
	v_and_b32_e32 v159, 0xffff0000, v159
	v_pk_mul_f32 v[160:161], v[204:205], v[160:161] op_sel_hi:[0,1]
	v_pk_mul_f32 v[158:159], v[204:205], v[158:159] op_sel_hi:[0,1]
	v_pk_fma_f32 v[42:43], v[134:135], v[42:43], v[160:161]
	v_add_u32_e32 v160, 0xa0, v188
	v_pk_fma_f32 v[50:51], v[138:139], v[50:51], v[158:159]
	v_lshlrev_b32_e32 v158, 16, v162
	v_and_b32_e32 v159, 0xffff0000, v162
	v_lshlrev_b32_e32 v162, 16, v164
	v_and_b32_e32 v163, 0xffff0000, v164
	v_lshlrev_b32_e32 v164, 16, v165
	v_and_b32_e32 v165, 0xffff0000, v165
	v_ashrrev_i32_e32 v161, 31, v160
	v_pk_mul_f32 v[166:167], v[204:205], v[166:167] op_sel_hi:[0,1]
	v_pk_mul_f32 v[168:169], v[204:205], v[168:169] op_sel_hi:[0,1]
	v_pk_mul_f32 v[158:159], v[204:205], v[158:159] op_sel_hi:[0,1]
	v_pk_mul_f32 v[162:163], v[204:205], v[162:163] op_sel_hi:[0,1]
	v_pk_mul_f32 v[164:165], v[204:205], v[164:165] op_sel_hi:[0,1]
	v_lshlrev_b64 v[154:155], 11, v[160:161]
	v_pk_fma_f32 v[48:49], v[136:137], v[48:49], v[166:167]
	v_pk_fma_f32 v[44:45], v[140:141], v[44:45], v[168:169]
	v_pk_fma_f32 v[40:41], v[132:133], v[40:41], v[158:159]
	v_pk_fma_f32 v[38:39], v[130:131], v[38:39], v[164:165]
	v_pk_fma_f32 v[36:37], v[128:129], v[36:37], v[162:163]
	v_lshl_add_u64 v[154:155], v[180:181], 0, v[154:155]
	global_load_dwordx4 v[162:165], v[154:155], off nt
	global_load_dwordx4 v[166:169], v[154:155], off offset:256 nt
	ds_read_b32 v158, v205 offset:4736
	s_waitcnt lgkmcnt(0)
	v_pk_mul_f32 v[34:35], v[34:35], v[158:159] op_sel_hi:[1,0]
	v_pk_mul_f32 v[24:25], v[24:25], v[158:159] op_sel_hi:[1,0]
	v_pk_mul_f32 v[30:31], v[30:31], v[158:159] op_sel_hi:[1,0]
	v_pk_mul_f32 v[32:33], v[32:33], v[158:159] op_sel_hi:[1,0]
	v_pk_mul_f32 v[28:29], v[28:29], v[158:159] op_sel_hi:[1,0]
	v_pk_mul_f32 v[26:27], v[26:27], v[158:159] op_sel_hi:[1,0]
	v_pk_mul_f32 v[20:21], v[20:21], v[158:159] op_sel_hi:[1,0]
	v_pk_mul_f32 v[22:23], v[22:23], v[158:159] op_sel_hi:[1,0]
	s_waitcnt vmcnt(1)
	v_lshlrev_b32_e32 v170, 16, v162
	v_and_b32_e32 v171, 0xffff0000, v162
	v_lshlrev_b32_e32 v162, 16, v163
	v_and_b32_e32 v163, 0xffff0000, v163
	v_pk_mul_f32 v[162:163], v[202:203], v[162:163] op_sel_hi:[0,1]
	v_pk_fma_f32 v[34:35], v[138:139], v[34:35], v[162:163]
	s_waitcnt vmcnt(0)
	v_lshlrev_b32_e32 v162, 16, v166
	v_and_b32_e32 v163, 0xffff0000, v166
	v_lshlrev_b32_e32 v172, 16, v164
	v_and_b32_e32 v173, 0xffff0000, v164
	v_lshlrev_b32_e32 v164, 16, v165
	v_and_b32_e32 v165, 0xffff0000, v165
	v_pk_mul_f32 v[162:163], v[202:203], v[162:163] op_sel_hi:[0,1]
	v_pk_mul_f32 v[164:165], v[202:203], v[164:165] op_sel_hi:[0,1]
	v_pk_fma_f32 v[24:25], v[132:133], v[24:25], v[162:163]
	v_add_u32_e32 v162, 0xb0, v188
	v_pk_fma_f32 v[30:31], v[142:143], v[30:31], v[164:165]
	v_lshlrev_b32_e32 v164, 16, v167
	v_and_b32_e32 v165, 0xffff0000, v167
	v_lshlrev_b32_e32 v166, 16, v168
	v_and_b32_e32 v167, 0xffff0000, v168
	v_lshlrev_b32_e32 v168, 16, v169
	v_and_b32_e32 v169, 0xffff0000, v169
	v_ashrrev_i32_e32 v163, 31, v162
	v_pk_mul_f32 v[170:171], v[202:203], v[170:171] op_sel_hi:[0,1]
	v_pk_mul_f32 v[172:173], v[202:203], v[172:173] op_sel_hi:[0,1]
	v_pk_mul_f32 v[164:165], v[202:203], v[164:165] op_sel_hi:[0,1]
	v_pk_mul_f32 v[166:167], v[202:203], v[166:167] op_sel_hi:[0,1]
	v_pk_mul_f32 v[168:169], v[202:203], v[168:169] op_sel_hi:[0,1]
	v_lshlrev_b64 v[158:159], 11, v[162:163]
	v_pk_fma_f32 v[32:33], v[136:137], v[32:33], v[170:171]
	v_pk_fma_f32 v[28:29], v[140:141], v[28:29], v[172:173]
	v_pk_fma_f32 v[26:27], v[134:135], v[26:27], v[164:165]
	v_pk_fma_f32 v[22:23], v[130:131], v[22:23], v[168:169]
	v_pk_fma_f32 v[20:21], v[128:129], v[20:21], v[166:167]
	v_lshl_add_u64 v[158:159], v[180:181], 0, v[158:159]
	global_load_dwordx4 v[166:169], v[158:159], off nt
	global_load_dwordx4 v[170:173], v[158:159], off offset:256 nt
	ds_read_b32 v174, v205 offset:4800
	v_lshlrev_b64 v[164:165], 10, v[188:189]
	s_waitcnt lgkmcnt(0)
	v_pk_mul_f32 v[16:17], v[16:17], v[174:175] op_sel_hi:[1,0]
	v_pk_mul_f32 v[18:19], v[18:19], v[174:175] op_sel_hi:[1,0]
	v_pk_mul_f32 v[12:13], v[12:13], v[174:175] op_sel_hi:[1,0]
	v_pk_mul_f32 v[14:15], v[14:15], v[174:175] op_sel_hi:[1,0]
	v_pk_mul_f32 v[8:9], v[8:9], v[174:175] op_sel_hi:[1,0]
	v_pk_mul_f32 v[10:11], v[10:11], v[174:175] op_sel_hi:[1,0]
	v_pk_mul_f32 v[4:5], v[4:5], v[174:175] op_sel_hi:[1,0]
	v_pk_mul_f32 v[6:7], v[6:7], v[174:175] op_sel_hi:[1,0]
	s_waitcnt vmcnt(1)
	v_lshlrev_b32_e32 v174, 16, v166
	v_and_b32_e32 v175, 0xffff0000, v166
	v_lshlrev_b32_e32 v166, 16, v167
	v_and_b32_e32 v167, 0xffff0000, v167
	v_lshlrev_b32_e32 v176, 16, v168
	v_and_b32_e32 v177, 0xffff0000, v168
	v_lshlrev_b32_e32 v168, 16, v169
	v_and_b32_e32 v169, 0xffff0000, v169
	s_waitcnt vmcnt(0)
	v_lshlrev_b32_e32 v178, 16, v170
	v_and_b32_e32 v179, 0xffff0000, v170
	v_lshlrev_b32_e32 v170, 16, v171
	v_and_b32_e32 v171, 0xffff0000, v171
	v_lshlrev_b32_e32 v188, 16, v172
	v_and_b32_e32 v189, 0xffff0000, v172
	v_lshlrev_b32_e32 v172, 16, v173
	v_and_b32_e32 v173, 0xffff0000, v173
	v_pk_mul_f32 v[174:175], v[2:3], v[174:175] op_sel_hi:[0,1]
	v_pk_mul_f32 v[166:167], v[2:3], v[166:167] op_sel_hi:[0,1]
	v_pk_mul_f32 v[176:177], v[2:3], v[176:177] op_sel_hi:[0,1]
	v_pk_mul_f32 v[168:169], v[2:3], v[168:169] op_sel_hi:[0,1]
	v_pk_mul_f32 v[178:179], v[2:3], v[178:179] op_sel_hi:[0,1]
	v_pk_mul_f32 v[170:171], v[2:3], v[170:171] op_sel_hi:[0,1]
	v_pk_mul_f32 v[188:189], v[2:3], v[188:189] op_sel_hi:[0,1]
	v_pk_mul_f32 v[172:173], v[2:3], v[172:173] op_sel_hi:[0,1]
	v_pk_fma_f32 v[18:19], v[138:139], v[18:19], v[166:167]
	v_pk_fma_f32 v[16:17], v[136:137], v[16:17], v[174:175]
	v_pk_fma_f32 v[14:15], v[142:143], v[14:15], v[168:169]
	v_pk_fma_f32 v[12:13], v[140:141], v[12:13], v[176:177]
	v_pk_fma_f32 v[10:11], v[134:135], v[10:11], v[170:171]
	v_pk_fma_f32 v[8:9], v[132:133], v[8:9], v[178:179]
	v_pk_fma_f32 v[6:7], v[130:131], v[6:7], v[172:173]
	v_pk_fma_f32 v[4:5], v[128:129], v[4:5], v[188:189]
	s_nop 0
	s_cbranch_vccz .LBB0_636
	v_lshl_add_u64 v[128:129], v[164:165], 0, v[0:1]
	v_lshl_add_u64 v[128:129], v[128:129], 2, s[4:5]
	global_store_dwordx4 v[128:129], v[144:147], off
	global_store_dwordx4 v[128:129], v[124:127], off offset:16
	global_store_dwordx4 v[128:129], v[120:123], off offset:512
	global_store_dwordx4 v[128:129], v[116:119], off offset:528
	s_mov_b64 s[0:1], 0
